# v56 + phase-1 epilogue output stores write-through only (sc1, no nt): isolates the two hints of v69
# baseline (speedup 1.0000x reference)
.LBB0_191:
	s_cmpk_lt_i32 s92, 0x80
	s_cselect_b64 s[0:1], -1, 0
	s_cmp_gt_i32 s52, 16
	s_cselect_b64 s[4:5], -1, 0
	s_and_b64 s[4:5], s[4:5], s[0:1]
	s_andn2_b64 vcc, exec, s[4:5]
	s_mov_b64 s[4:5], -1
	s_cbranch_vccz .LBB0_209
	s_ashr_i32 s16, s52, 2
	s_cmp_eq_u32 s16, 2
	s_mov_b32 s4, 0xfc00000
	s_cselect_b32 s4, s4, 0x13d00000
	s_cmp_lg_u32 s16, 1
	s_cselect_b32 s4, s4, 0xbb00000
	s_cmp_gt_u32 s52, 3
	s_cselect_b32 s54, s4, 0x7a00000
	s_add_u32 s34, s76, s54
	s_addc_u32 s35, s77, 0
	s_and_b64 s[0:1], s[0:1], exec
	v_readlane_b32 s56, v255, 0
	v_readlane_b32 s63, v255, 7
	v_readlane_b32 s0, v255, 37
	v_readlane_b32 s4, v255, 39
	v_readlane_b32 s5, v255, 41
	v_readlane_b32 s62, v255, 6
	s_cselect_b32 s1, s63, s0
	v_readlane_b32 s0, v255, 36
	s_cselect_b32 s39, s4, s5
	v_readlane_b32 s4, v255, 38
	v_readlane_b32 s5, v255, 40
	s_cselect_b32 s0, s62, s0
	s_cselect_b32 s38, s4, s5
	s_lshl_b32 s55, s92, 8
	s_add_i32 s55, s55, s81
	s_cmp_gt_i32 s52, 16
	s_cselect_b64 s[4:5], -1, 0
	s_cmp_eq_u32 s52, 16
	v_lshl_add_u32 v140, s52, 6, v159
	s_cselect_b64 s[12:13], -1, 0
	s_cmp_lg_u32 s52, 16
	v_lshlrev_b32_e32 v179, 1, v140
	s_cselect_b64 s[10:11], -1, 0
	v_or_b32_e32 v156, s55, v158
	s_mov_b64 s[14:15], -1
	s_and_b64 vcc, exec, s[4:5]
	v_readlane_b32 s57, v255, 1
	v_readlane_b32 s58, v255, 2
	v_readlane_b32 s59, v255, 3
	v_readlane_b32 s60, v255, 4
	v_readlane_b32 s61, v255, 5
	s_cbranch_vccz .LBB0_194
	v_mul_f32_e32 v128, 0xbfb8aa3b, v80
	v_mul_f32_e32 v129, 0xbfb8aa3b, v81
	v_mul_f32_e32 v130, 0xbfb8aa3b, v82
	v_mul_f32_e32 v131, 0xbfb8aa3b, v83
	v_exp_f32_e32 v128, v128
	v_exp_f32_e32 v129, v129
	v_exp_f32_e32 v130, v130
	v_exp_f32_e32 v131, v131
	v_add_f32_e32 v128, 1.0, v128
	v_add_f32_e32 v129, 1.0, v129
	v_add_f32_e32 v130, 1.0, v130
	v_add_f32_e32 v131, 1.0, v131
	v_rcp_f32_e32 v128, v128
	v_rcp_f32_e32 v130, v130
	v_rcp_f32_e32 v131, v131
	v_rcp_f32_e32 v129, v129
	v_pk_mul_f32 v[152:153], v[94:95], v[90:91]
	v_pk_mul_f32 v[154:155], v[92:93], v[88:89]
	v_pk_mul_f32 v[130:131], v[82:83], v[130:131]
	v_pk_mul_f32 v[128:129], v[80:81], v[128:129]
	v_pk_mul_f32 v[130:131], v[86:87], v[130:131]
	v_pk_mul_f32 v[128:129], v[84:85], v[128:129]
	v_lshl_add_u32 v157, v156, 11, v179
	v_cvt_pk_f16_f32 v153, v152, v153
	v_cvt_pk_f16_f32 v152, v154, v155
	v_cvt_pk_f16_f32 v131, v130, v131
	v_cvt_pk_f16_f32 v130, v128, v129
	global_store_dwordx2 v157, v[152:153], s[0:1] sc1
	global_store_dwordx2 v157, v[130:131], s[38:39] sc1
	s_mov_b64 s[14:15], 0
.LBB0_194:
	s_lshl_b32 s17, s52, 8
	v_cndmask_b32_e64 v128, 0, 1, s[10:11]
	s_and_b32 s53, s17, 0x300
	s_andn2_b64 vcc, exec, s[14:15]
	v_cmp_ne_u32_e64 s[10:11], 1, v128
	s_cbranch_vccnz .LBB0_197
	v_lshlrev_b32_e32 v128, 10, v156
	s_and_b64 s[14:15], s[12:13], exec
	v_or3_b32 v128, v128, s53, v142
	s_cselect_b32 s14, 0x17e00000, s54
	v_lshl_or_b32 v129, v156, 8, v160
	v_lshlrev_b32_e32 v128, 1, v128
	s_cselect_b32 s15, 0, 0
	s_add_u32 s14, s76, s14
	v_cvt_pk_f16_f32 v155, v94, v95
	v_cvt_pk_f16_f32 v154, v92, v93
	v_cvt_pk_f16_f32 v153, v86, v87
	v_cvt_pk_f16_f32 v152, v84, v85
	v_cndmask_b32_e64 v129, v128, v129, s[12:13]
	s_addc_u32 s15, s77, s15
	s_and_b64 vcc, exec, s[10:11]
	global_store_dwordx4 v129, v[152:155], s[14:15] sc1
	s_cbranch_vccnz .LBB0_197
	s_nop 0
	v_cvt_pk_f16_f32 v155, v82, v83
	v_cvt_pk_f16_f32 v154, v80, v81
	v_cvt_pk_f16_f32 v153, v90, v91
	v_cvt_pk_f16_f32 v152, v88, v89
	global_store_dwordx4 v128, v[152:155], s[34:35] offset:256 sc1
.LBB0_197:
	v_cndmask_b32_e64 v129, 0, 1, s[4:5]
	v_or_b32_e32 v128, 1, v156
	v_cmp_ne_u32_e64 s[14:15], 1, v129
	s_andn2_b64 vcc, exec, s[4:5]
	s_mov_b64 s[4:5], -1
	s_cbranch_vccnz .LBB0_199
	v_mul_f32_e32 v129, 0xbfb8aa3b, v64
	v_exp_f32_e32 v129, v129
	v_mul_f32_e32 v130, 0xbfb8aa3b, v65
	v_mul_f32_e32 v131, 0xbfb8aa3b, v66
	v_exp_f32_e32 v152, v130
	v_add_f32_e32 v129, 1.0, v129
	v_rcp_f32_e32 v130, v129
	v_exp_f32_e32 v129, v131
	v_mul_f32_e32 v131, 0xbfb8aa3b, v67
	v_exp_f32_e32 v131, v131
	v_add_f32_e32 v154, 1.0, v152
	v_add_f32_e32 v129, 1.0, v129
	v_rcp_f32_e32 v152, v129
	v_add_f32_e32 v129, 1.0, v131
	v_rcp_f32_e32 v153, v129
	v_rcp_f32_e32 v131, v154
	v_pk_mul_f32 v[154:155], v[78:79], v[74:75]
	v_pk_mul_f32 v[180:181], v[76:77], v[72:73]
	v_pk_mul_f32 v[152:153], v[66:67], v[152:153]
	v_pk_mul_f32 v[130:131], v[64:65], v[130:131]
	v_pk_mul_f32 v[152:153], v[70:71], v[152:153]
	v_pk_mul_f32 v[130:131], v[68:69], v[130:131]
	v_lshl_add_u32 v129, v128, 11, v179
	v_cvt_pk_f16_f32 v155, v154, v155
	v_cvt_pk_f16_f32 v154, v180, v181
	v_cvt_pk_f16_f32 v153, v152, v153
	v_cvt_pk_f16_f32 v152, v130, v131
	s_mov_b64 s[4:5], 0
	global_store_dwordx2 v129, v[154:155], s[0:1] sc1
	global_store_dwordx2 v129, v[152:153], s[38:39] sc1
.LBB0_199:
	s_andn2_b64 vcc, exec, s[4:5]
	s_cbranch_vccnz .LBB0_202
	v_lshlrev_b32_e32 v129, 10, v128
	s_and_b64 s[4:5], s[12:13], exec
	v_lshl_or_b32 v130, v128, 8, v160
	v_or3_b32 v128, v129, s53, v142
	s_cselect_b32 s4, 0x17e00000, s54
	v_lshlrev_b32_e32 v128, 1, v128
	s_cselect_b32 s5, 0, 0
	s_add_u32 s4, s76, s4
	v_cvt_pk_f16_f32 v155, v78, v79
	v_cvt_pk_f16_f32 v154, v76, v77
	v_cvt_pk_f16_f32 v153, v70, v71
	v_cvt_pk_f16_f32 v152, v68, v69
	v_cndmask_b32_e64 v129, v128, v130, s[12:13]
	s_addc_u32 s5, s77, s5
	s_and_b64 vcc, exec, s[10:11]
	global_store_dwordx4 v129, v[152:155], s[4:5] sc1
	s_cbranch_vccnz .LBB0_202
	s_nop 0
	v_cvt_pk_f16_f32 v155, v66, v67
	v_cvt_pk_f16_f32 v154, v64, v65
	v_cvt_pk_f16_f32 v153, v74, v75
	v_cvt_pk_f16_f32 v152, v72, v73
	global_store_dwordx4 v128, v[152:155], s[34:35] offset:256 sc1

.LBB0_206:
	v_mul_f32_e32 v128, 0xbfb8aa3b, v48
	v_mul_f32_e32 v129, 0xbfb8aa3b, v49
	v_mul_f32_e32 v130, 0xbfb8aa3b, v50
	v_mul_f32_e32 v131, 0xbfb8aa3b, v51
	v_exp_f32_e32 v128, v128
	v_exp_f32_e32 v129, v129
	v_exp_f32_e32 v130, v130
	v_exp_f32_e32 v131, v131
	v_add_f32_e32 v128, 1.0, v128
	v_add_f32_e32 v129, 1.0, v129
	v_add_f32_e32 v130, 1.0, v130
	v_add_f32_e32 v131, 1.0, v131
	v_rcp_f32_e32 v128, v128
	v_rcp_f32_e32 v130, v130
	v_rcp_f32_e32 v131, v131
	v_rcp_f32_e32 v129, v129
	v_lshl_add_u32 v181, v180, 11, v179
	v_cmp_lt_i32_e32 vcc, -1, v153
	v_pk_mul_f32 v[130:131], v[50:51], v[130:131]
	v_pk_mul_f32 v[128:129], v[48:49], v[128:129]
	v_pk_mul_f32 v[184:185], v[54:55], v[130:131]
	v_pk_mul_f32 v[182:183], v[52:53], v[128:129]
	v_pk_mul_f32 v[130:131], v[126:127], v[122:123]
	v_pk_mul_f32 v[128:129], v[124:125], v[120:121]
	v_cvt_pk_f16_f32 v187, v130, v131
	v_cvt_pk_f16_f32 v186, v128, v129
	v_cvt_pk_f16_f32 v185, v184, v185
	v_cvt_pk_f16_f32 v184, v182, v183
	global_store_dwordx2 v181, v[186:187], s[0:1] sc1
	global_store_dwordx2 v181, v[184:185], s[38:39] sc1
	s_and_saveexec_b64 s[4:5], vcc
	s_cbranch_execz .LBB0_208
	v_readlane_b32 s56, v255, 0
	v_readlane_b32 s62, v255, 6
	v_readlane_b32 s63, v255, 7
	v_ashrrev_i32_e32 v153, 31, v152
	v_lshlrev_b64 v[152:153], 13, v[152:153]
	v_lshl_add_u64 v[154:155], v[154:155], 2, s[62:63]
	v_lshl_add_u64 v[152:153], v[154:155], 0, v[152:153]
	v_lshl_add_u64 v[152:153], v[140:141], 2, v[152:153]
	v_readlane_b32 s57, v255, 1
	v_readlane_b32 s58, v255, 2
	v_readlane_b32 s59, v255, 3
	v_readlane_b32 s60, v255, 4
	v_readlane_b32 s61, v255, 5
	global_store_dwordx4 v[152:153], v[128:131], off sc1

.LBB0_209:
	s_and_b64 vcc, exec, s[4:5]
	s_cbranch_vccz .LBB0_302
	s_lshl_b32 s4, s92, 8
	s_add_i32 s4, s4, s81
	s_and_b32 s0, s4, 0xfc0
	v_or_b32_e32 v128, s0, v158
	s_movk_i32 s0, 0xffc
	v_lshl_add_u32 v140, s52, 6, v159
	v_pk_mul_f32 v[122:123], v[126:127], v[122:123]
	v_pk_mul_f32 v[120:121], v[124:125], v[120:121]
	v_cmp_eq_u32_e32 vcc, s0, v128
	s_and_saveexec_b64 s[0:1], vcc
	s_cbranch_execz .LBB0_212
	s_ashr_i32 s10, s4, 12
	s_ashr_i32 s11, s10, 31
	s_lshl_b64 s[10:11], s[10:11], 13
	v_readlane_b32 s5, v255, 44
	s_add_u32 s10, s5, s10
	v_readlane_b32 s5, v255, 45
	s_addc_u32 s11, s5, s11
	v_lshl_add_u64 v[124:125], v[140:141], 2, s[10:11]
	global_store_dwordx4 v[124:125], v[120:123], off sc1
.LBB0_212:
	s_or_b64 exec, exec, s[0:1]
	s_movk_i32 s0, 0xffa
	v_pk_mul_f32 v[118:119], v[118:119], v[114:115]
	v_pk_mul_f32 v[116:117], v[116:117], v[112:113]
	v_cmp_lt_u32_e32 vcc, s0, v128
	s_and_saveexec_b64 s[0:1], vcc
	s_cbranch_execz .LBB0_214
	s_ashr_i32 s10, s4, 12
	s_ashr_i32 s11, s10, 31
	s_lshl_b64 s[10:11], s[10:11], 13
	v_readlane_b32 s5, v255, 44
	v_add_u32_e32 v112, 0xfffff005, v128
	v_mov_b32_e32 v113, v141
	s_add_u32 s10, s5, s10
	v_readlane_b32 s5, v255, 45
	s_addc_u32 s11, s5, s11
	v_lshlrev_b64 v[112:113], 12, v[112:113]
	v_lshl_add_u64 v[112:113], s[10:11], 0, v[112:113]
	v_lshl_add_u64 v[112:113], v[140:141], 2, v[112:113]
	global_store_dwordx4 v[112:113], v[116:119], off sc1
.LBB0_214:
	s_or_b64 exec, exec, s[0:1]
	s_addk_i32 s4, 0x80
	s_and_b32 s0, s4, 0xfc0
	v_or_b32_e32 v112, s0, v158
	s_movk_i32 s0, 0xffc
	v_pk_mul_f32 v[106:107], v[110:111], v[106:107]
	v_pk_mul_f32 v[104:105], v[108:109], v[104:105]
	v_cmp_eq_u32_e32 vcc, s0, v112
	s_and_saveexec_b64 s[0:1], vcc
	s_cbranch_execz .LBB0_216
	s_ashr_i32 s10, s4, 12
	s_ashr_i32 s11, s10, 31
	s_lshl_b64 s[10:11], s[10:11], 13
	v_readlane_b32 s5, v255, 44
	s_add_u32 s10, s5, s10
	v_readlane_b32 s5, v255, 45
	s_addc_u32 s11, s5, s11
	v_lshl_add_u64 v[108:109], v[140:141], 2, s[10:11]
	global_store_dwordx4 v[108:109], v[104:107], off sc1
.LBB0_216:
	s_or_b64 exec, exec, s[0:1]
	s_movk_i32 s0, 0xffa
	v_pk_mul_f32 v[98:99], v[102:103], v[98:99]
	v_pk_mul_f32 v[96:97], v[100:101], v[96:97]
	v_cmp_lt_u32_e32 vcc, s0, v112
	s_and_saveexec_b64 s[0:1], vcc
	s_cbranch_execz .LBB0_218
	s_ashr_i32 s4, s4, 12
	s_ashr_i32 s5, s4, 31
	s_lshl_b64 s[4:5], s[4:5], 13
	v_readlane_b32 s10, v255, 44
	v_add_u32_e32 v100, 0xfffff005, v112
	v_mov_b32_e32 v101, v141
	s_add_u32 s4, s10, s4
	v_readlane_b32 s10, v255, 45
	s_addc_u32 s5, s10, s5
	v_lshlrev_b64 v[100:101], 12, v[100:101]
	v_lshl_add_u64 v[100:101], s[4:5], 0, v[100:101]
	v_lshl_add_u64 v[100:101], v[140:141], 2, v[100:101]
	global_store_dwordx4 v[100:101], v[96:99], off sc1
.LBB0_218:
	s_or_b64 exec, exec, s[0:1]
	s_mov_b64 s[0:1], exec
	v_readlane_b32 s4, v255, 56
	v_readlane_b32 s5, v255, 57
	s_and_b64 s[4:5], s[0:1], s[4:5]
	s_mov_b64 exec, s[4:5]
	s_cbranch_execz .LBB0_221
	s_and_b64 vcc, exec, s[70:71]
	ds_write_b128 v165, v[120:123]
	ds_write_b128 v165, v[116:119] offset:256
	ds_write_b128 v165, v[104:107] offset:1024
	ds_write_b128 v165, v[96:99] offset:1280
	s_cbranch_vccz .LBB0_221
	s_ashr_i32 s93, s92, 31
	s_lshl_b64 s[4:5], s[92:93], 13
	v_readlane_b32 s10, v255, 46
	s_add_u32 s4, s10, s4
	v_readlane_b32 s10, v255, 47
	s_addc_u32 s5, s10, s5
	v_lshl_add_u64 v[100:101], v[140:141], 2, s[4:5]
	global_store_dwordx4 v[100:101], v[104:107], off sc1
	v_add_co_u32_e32 v100, vcc, 0x1000, v100
	s_nop 1
	v_addc_co_u32_e32 v101, vcc, 0, v101, vcc
	global_store_dwordx4 v[100:101], v[96:99], off sc1

.LBB0_223:
	s_or_b64 exec, exec, s[0:1]
	v_pk_mul_f32 v[90:91], v[94:95], v[90:91]
	v_pk_mul_f32 v[88:89], v[92:93], v[88:89]
	v_mul_f32_e32 v92, 0xbfb8aa3b, v80
	v_mul_f32_e32 v93, 0xbfb8aa3b, v81
	v_mul_f32_e32 v94, 0xbfb8aa3b, v82
	v_mul_f32_e32 v95, 0xbfb8aa3b, v83
	v_exp_f32_e32 v92, v92
	v_exp_f32_e32 v93, v93
	v_exp_f32_e32 v94, v94
	v_exp_f32_e32 v95, v95
	v_add_f32_e32 v92, 1.0, v92
	v_add_f32_e32 v93, 1.0, v93
	v_add_f32_e32 v94, 1.0, v94
	v_add_f32_e32 v95, 1.0, v95
	v_rcp_f32_e32 v92, v92
	v_rcp_f32_e32 v93, v93
	v_rcp_f32_e32 v94, v94
	v_rcp_f32_e32 v95, v95
	s_and_b32 s0, s92, 15
	v_pk_mul_f32 v[80:81], v[80:81], v[92:93]
	s_cmp_lg_u32 s0, 0
	v_pk_mul_f32 v[82:83], v[82:83], v[94:95]
	v_pk_mul_f32 v[80:81], v[84:85], v[80:81]
	v_pk_mul_f32 v[82:83], v[86:87], v[82:83]
	s_waitcnt vmcnt(0) lgkmcnt(0)
	v_pk_mul_f32 v[84:85], v[110:111], v[126:127]
	v_pk_mul_f32 v[86:87], v[108:109], v[124:125]
	v_pk_fma_f32 v[84:85], v[90:91], v[114:115], v[84:85]
	v_pk_fma_f32 v[92:93], v[88:89], v[112:113], v[86:87]
	v_readlane_b32 s4, v255, 62
	s_cselect_b64 s[0:1], -1, 0
	v_pk_fma_f32 v[86:87], v[102:103], v[130:131], v[84:85]
	v_pk_fma_f32 v[84:85], v[100:101], v[128:129], v[92:93]
	v_readlane_b32 s5, v255, 63
	s_and_b64 s[0:1], s[4:5], s[0:1]
	v_pk_mul_f32 v[84:85], v[80:81], v[84:85]
	s_and_saveexec_b64 s[4:5], s[0:1]
	s_xor_b64 s[4:5], exec, s[4:5]
	s_cbranch_execz .LBB0_225
	s_ashr_i32 s93, s92, 31
	s_lshl_b64 s[10:11], s[92:93], 13
	v_readlane_b32 s12, v255, 52
	s_add_u32 s12, s12, s10
	v_readlane_b32 s13, v255, 53
	s_addc_u32 s13, s13, s11
	v_pk_mul_f32 v[86:87], v[82:83], v[86:87]
	v_lshl_add_u64 v[92:93], s[12:13], 0, v[152:153]
	v_readlane_b32 s12, v255, 54
	s_add_u32 s10, s12, s10
	v_readlane_b32 s12, v255, 55
	s_addc_u32 s11, s12, s11
	v_lshl_add_u64 v[94:95], s[10:11], 0, v[152:153]
	global_store_dwordx4 v[92:93], v[84:87], off sc1
	global_store_dwordx4 v[94:95], v[80:83], off sc1
.LBB0_225:
	s_or_saveexec_b64 s[4:5], s[4:5]
	s_nop 0
	v_lshlrev_b32_e32 v80, 1, v140
	s_xor_b64 exec, exec, s[4:5]
	s_cbranch_execz .LBB0_227
	v_pk_mul_f32 v[82:83], v[82:83], v[86:87]
	s_lshl_b32 s10, s92, 19
	v_cvt_pk_f16_f32 v83, v82, v83
	v_cvt_pk_f16_f32 v82, v84, v85
	v_add3_u32 v81, s10, v163, v80
	global_store_dwordx2 v81, v[82:83], s[84:85] sc1
.LBB0_227:
	s_or_b64 exec, exec, s[4:5]
	v_pk_mul_f32 v[74:75], v[78:79], v[74:75]
	v_pk_mul_f32 v[72:73], v[76:77], v[72:73]
	v_mul_f32_e32 v76, 0xbfb8aa3b, v64
	v_mul_f32_e32 v77, 0xbfb8aa3b, v65
	v_mul_f32_e32 v78, 0xbfb8aa3b, v66
	v_mul_f32_e32 v79, 0xbfb8aa3b, v67
	v_exp_f32_e32 v76, v76
	v_exp_f32_e32 v77, v77
	v_exp_f32_e32 v78, v78
	v_exp_f32_e32 v79, v79
	v_add_f32_e32 v76, 1.0, v76
	v_add_f32_e32 v77, 1.0, v77
	v_add_f32_e32 v78, 1.0, v78
	v_add_f32_e32 v79, 1.0, v79
	v_rcp_f32_e32 v76, v76
	v_rcp_f32_e32 v77, v77
	v_rcp_f32_e32 v78, v78
	v_rcp_f32_e32 v79, v79
	v_pk_mul_f32 v[64:65], v[64:65], v[76:77]
	s_nop 0
	v_pk_mul_f32 v[64:65], v[68:69], v[64:65]
	v_pk_mul_f32 v[66:67], v[66:67], v[78:79]
	v_pk_mul_f32 v[68:69], v[74:75], v[114:115]
	v_pk_mul_f32 v[66:67], v[70:71], v[66:67]
	v_pk_mul_f32 v[70:71], v[72:73], v[112:113]
	v_pk_fma_f32 v[68:69], v[90:91], v[110:111], v[68:69]
	v_pk_fma_f32 v[76:77], v[88:89], v[108:109], v[70:71]
	v_pk_fma_f32 v[70:71], v[102:103], v[126:127], v[68:69]
	v_pk_fma_f32 v[68:69], v[100:101], v[124:125], v[76:77]
	s_nop 0
	v_pk_mul_f32 v[68:69], v[64:65], v[68:69]
	s_and_saveexec_b64 s[10:11], s[0:1]
	s_xor_b64 s[0:1], exec, s[10:11]
	s_cbranch_execz .LBB0_229
	s_ashr_i32 s93, s92, 31
	s_lshl_b64 s[4:5], s[92:93], 13
	s_add_u32 s4, s76, s4
	s_addc_u32 s5, s77, s5
	v_lshl_add_u64 v[76:77], v[140:141], 2, s[4:5]
	v_add_co_u32_e32 v78, vcc, 0x1c901000, v76
	v_pk_mul_f32 v[70:71], v[66:67], v[70:71]
	s_nop 0
	v_addc_co_u32_e32 v79, vcc, 0, v77, vcc
	global_store_dwordx4 v[78:79], v[68:71], off sc1
	s_lshl_b32 s4, s92, 19
	s_nop 0
	v_add_co_u32_e32 v68, vcc, 0x1ca01000, v76
	s_nop 1
	v_addc_co_u32_e32 v69, vcc, 0, v77, vcc
	global_store_dwordx4 v[68:69], v[64:67], off sc1
.LBB0_229:
	s_or_saveexec_b64 s[0:1], s[0:1]
	s_nop 0
	v_mov_b32_e32 v64, 0
	v_mov_b32_e32 v65, s4
	s_xor_b64 exec, exec, s[0:1]
	s_cbranch_execz .LBB0_231
	v_pk_mul_f32 v[64:65], v[66:67], v[70:71]
	s_lshl_b32 s4, s92, 19
	v_cvt_pk_f16_f32 v65, v64, v65
	v_cvt_pk_f16_f32 v64, v68, v69
	v_add3_u32 v66, v164, s4, v80
	global_store_dwordx2 v66, v[64:65], s[84:85] sc1
	v_mov_b32_e32 v65, s4
	v_mov_b32_e32 v64, v163
.LBB0_231:
	s_or_b64 exec, exec, s[0:1]
	v_mul_f32_e32 v66, 0xbfb8aa3b, v56
	v_mul_f32_e32 v67, 0xbfb8aa3b, v57
	v_mul_f32_e32 v68, 0xbfb8aa3b, v58
	v_mul_f32_e32 v69, 0xbfb8aa3b, v59
	v_exp_f32_e32 v66, v66
	v_exp_f32_e32 v67, v67
	v_exp_f32_e32 v68, v68
	v_exp_f32_e32 v69, v69
	v_add_f32_e32 v66, 1.0, v66
	v_add_f32_e32 v67, 1.0, v67
	v_add_f32_e32 v68, 1.0, v68
	v_add_f32_e32 v69, 1.0, v69
	v_rcp_f32_e32 v66, v66
	v_rcp_f32_e32 v67, v67
	v_rcp_f32_e32 v68, v68
	v_rcp_f32_e32 v69, v69
	v_pk_mul_f32 v[56:57], v[56:57], v[66:67]
	s_nop 0
	v_pk_mul_f32 v[60:61], v[60:61], v[56:57]
	v_pk_mul_f32 v[58:59], v[58:59], v[68:69]
	v_mul_f32_e32 v56, 0xbfb8aa3b, v48
	v_pk_mul_f32 v[58:59], v[62:63], v[58:59]
	v_mul_f32_e32 v57, 0xbfb8aa3b, v49
	v_mul_f32_e32 v62, 0xbfb8aa3b, v50
	v_mul_f32_e32 v63, 0xbfb8aa3b, v51
	v_exp_f32_e32 v56, v56
	v_exp_f32_e32 v57, v57
	v_exp_f32_e32 v62, v62
	v_exp_f32_e32 v63, v63
	v_add_f32_e32 v56, 1.0, v56
	v_add_f32_e32 v57, 1.0, v57
	v_add_f32_e32 v62, 1.0, v62
	v_add_f32_e32 v63, 1.0, v63
	v_rcp_f32_e32 v56, v56
	v_rcp_f32_e32 v57, v57
	v_rcp_f32_e32 v62, v62
	v_rcp_f32_e32 v63, v63
	v_pk_mul_f32 v[48:49], v[48:49], v[56:57]
	s_nop 0
	v_pk_mul_f32 v[48:49], v[52:53], v[48:49]
	v_pk_mul_f32 v[50:51], v[50:51], v[62:63]
	v_pk_mul_f32 v[52:53], v[122:123], v[114:115]
	v_pk_mul_f32 v[50:51], v[54:55], v[50:51]
	v_pk_mul_f32 v[54:55], v[120:121], v[112:113]
	v_pk_fma_f32 v[52:53], v[74:75], v[110:111], v[52:53]
	v_pk_fma_f32 v[54:55], v[72:73], v[108:109], v[54:55]
	v_pk_fma_f32 v[52:53], v[90:91], v[102:103], v[52:53]
	v_pk_fma_f32 v[54:55], v[88:89], v[100:101], v[54:55]
	v_pk_mul_f32 v[50:51], v[50:51], v[52:53]
	v_pk_mul_f32 v[48:49], v[48:49], v[54:55]
	v_cvt_pk_f16_f32 v51, v50, v51
	v_cvt_pk_f16_f32 v50, v48, v49
	v_add_u32_e32 v48, v65, v64
	v_add_u32_e32 v56, v80, v48
	v_add_u32_e32 v48, 0x1000, v56
	global_store_dwordx2 v48, v[50:51], s[84:85] sc1
	v_pk_mul_f32 v[48:49], v[118:119], v[114:115]
	v_pk_mul_f32 v[50:51], v[116:117], v[112:113]
	v_pk_fma_f32 v[48:49], v[122:123], v[110:111], v[48:49]
	v_pk_fma_f32 v[50:51], v[120:121], v[108:109], v[50:51]
	v_pk_fma_f32 v[48:49], v[74:75], v[102:103], v[48:49]
	v_pk_fma_f32 v[50:51], v[72:73], v[100:101], v[50:51]
	v_pk_mul_f32 v[48:49], v[58:59], v[48:49]
	v_pk_mul_f32 v[50:51], v[60:61], v[50:51]
	v_cvt_pk_f16_f32 v49, v48, v49
	v_cvt_pk_f16_f32 v48, v50, v51
	v_add_u32_e32 v50, 0x1800, v56
	global_store_dwordx2 v50, v[48:49], s[84:85] sc1
	v_mov_b32_dpp v48, v96 row_shr:1 row_mask:0xf bank_mask:0xf bound_ctrl:1
	v_mov_b32_dpp v52, v104 row_shr:1 row_mask:0xf bank_mask:0xf bound_ctrl:1
	v_mov_b32_dpp v49, v97 row_shr:1 row_mask:0xf bank_mask:0xf bound_ctrl:1
	v_mov_b32_dpp v53, v105 row_shr:1 row_mask:0xf bank_mask:0xf bound_ctrl:1
	v_mov_b32_dpp v50, v98 row_shr:1 row_mask:0xf bank_mask:0xf bound_ctrl:1
	v_mov_b32_dpp v54, v106 row_shr:1 row_mask:0xf bank_mask:0xf bound_ctrl:1
	v_mov_b32_dpp v51, v99 row_shr:1 row_mask:0xf bank_mask:0xf bound_ctrl:1
	v_mov_b32_dpp v55, v107 row_shr:1 row_mask:0xf bank_mask:0xf bound_ctrl:1
	s_mov_b64 s[0:1], exec
	v_readlane_b32 s4, v255, 58
	v_readlane_b32 s5, v255, 59
	s_and_b64 s[4:5], s[0:1], s[4:5]
	s_mov_b64 exec, s[4:5]
	s_cbranch_execz .LBB0_233
	ds_read_b128 v[52:55], v165 offset:512
	ds_read_b128 v[48:51], v165 offset:768
.LBB0_233:
	s_or_b64 exec, exec, s[0:1]
	v_pk_mul_f32 v[26:27], v[34:35], v[26:27]
	v_pk_mul_f32 v[24:25], v[32:33], v[24:25]
	v_mul_f32_e32 v32, 0xbfb8aa3b, v16
	v_mul_f32_e32 v33, 0xbfb8aa3b, v17
	v_mul_f32_e32 v34, 0xbfb8aa3b, v18
	v_mul_f32_e32 v35, 0xbfb8aa3b, v19
	v_exp_f32_e32 v32, v32
	v_exp_f32_e32 v33, v33
	v_exp_f32_e32 v34, v34
	v_exp_f32_e32 v35, v35
	v_pk_mul_f32 v[42:43], v[46:47], v[42:43]
	v_pk_mul_f32 v[40:41], v[44:45], v[40:41]
	v_mul_f32_e32 v44, 0xbfb8aa3b, v28
	v_mul_f32_e32 v45, 0xbfb8aa3b, v29
	v_mul_f32_e32 v46, 0xbfb8aa3b, v30
	v_mul_f32_e32 v47, 0xbfb8aa3b, v31
	v_exp_f32_e32 v44, v44
	v_exp_f32_e32 v45, v45
	v_exp_f32_e32 v46, v46
	v_exp_f32_e32 v47, v47
	v_add_f32_e32 v32, 1.0, v32
	v_add_f32_e32 v33, 1.0, v33
	v_add_f32_e32 v34, 1.0, v34
	v_add_f32_e32 v35, 1.0, v35
	v_rcp_f32_e32 v32, v32
	v_rcp_f32_e32 v33, v33
	v_rcp_f32_e32 v34, v34
	v_rcp_f32_e32 v35, v35
	v_add_f32_e32 v44, 1.0, v44
	v_add_f32_e32 v45, 1.0, v45
	v_add_f32_e32 v46, 1.0, v46
	v_add_f32_e32 v47, 1.0, v47
	v_rcp_f32_e32 v44, v44
	v_rcp_f32_e32 v45, v45
	v_rcp_f32_e32 v46, v46
	v_rcp_f32_e32 v47, v47
	v_pk_mul_f32 v[16:17], v[16:17], v[32:33]
	v_pk_mul_f32 v[18:19], v[18:19], v[34:35]
	v_pk_mul_f32 v[16:17], v[20:21], v[16:17]
	v_pk_mul_f32 v[18:19], v[22:23], v[18:19]
	s_waitcnt lgkmcnt(0)
	v_pk_mul_f32 v[20:21], v[110:111], v[50:51]
	v_pk_mul_f32 v[22:23], v[108:109], v[48:49]
	v_pk_mul_f32 v[28:29], v[28:29], v[44:45]
	v_pk_mul_f32 v[30:31], v[30:31], v[46:47]
	v_pk_fma_f32 v[20:21], v[42:43], v[114:115], v[20:21]
	v_pk_fma_f32 v[22:23], v[40:41], v[112:113], v[22:23]
	v_pk_mul_f32 v[30:31], v[38:39], v[30:31]
	v_pk_mul_f32 v[28:29], v[36:37], v[28:29]
	v_pk_fma_f32 v[20:21], v[102:103], v[54:55], v[20:21]
	v_pk_fma_f32 v[22:23], v[100:101], v[52:53], v[22:23]
	v_pk_mul_f32 v[20:21], v[30:31], v[20:21]
	v_pk_mul_f32 v[22:23], v[28:29], v[22:23]
	v_cvt_pk_f16_f32 v21, v20, v21
	v_cvt_pk_f16_f32 v20, v22, v23
	v_add_u32_e32 v22, 0x40000, v56
	global_store_dwordx2 v22, v[20:21], s[84:85] sc1
	v_pk_mul_f32 v[20:21], v[26:27], v[114:115]
	v_pk_mul_f32 v[22:23], v[24:25], v[112:113]
	v_pk_fma_f32 v[20:21], v[42:43], v[110:111], v[20:21]
	v_pk_fma_f32 v[22:23], v[40:41], v[108:109], v[22:23]
	v_pk_fma_f32 v[20:21], v[102:103], v[50:51], v[20:21]
	v_pk_fma_f32 v[22:23], v[100:101], v[48:49], v[22:23]
	v_pk_mul_f32 v[18:19], v[18:19], v[20:21]
	v_pk_mul_f32 v[16:17], v[16:17], v[22:23]
	v_cvt_pk_f16_f32 v19, v18, v19
	v_cvt_pk_f16_f32 v18, v16, v17
	v_add_u32_e32 v16, 0x40800, v56
	global_store_dwordx2 v16, v[18:19], s[84:85] sc1
	v_mul_f32_e32 v16, 0xbfb8aa3b, v8
	v_mul_f32_e32 v17, 0xbfb8aa3b, v9
	v_mul_f32_e32 v18, 0xbfb8aa3b, v10
	v_mul_f32_e32 v19, 0xbfb8aa3b, v11
	v_exp_f32_e32 v16, v16
	v_exp_f32_e32 v17, v17
	v_exp_f32_e32 v18, v18
	v_exp_f32_e32 v19, v19
	v_add_f32_e32 v16, 1.0, v16
	v_add_f32_e32 v17, 1.0, v17
	v_add_f32_e32 v18, 1.0, v18
	v_add_f32_e32 v19, 1.0, v19
	v_rcp_f32_e32 v16, v16
	v_rcp_f32_e32 v17, v17
	v_rcp_f32_e32 v18, v18
	v_rcp_f32_e32 v19, v19
	v_pk_mul_f32 v[8:9], v[8:9], v[16:17]
	s_nop 0
	v_pk_mul_f32 v[8:9], v[12:13], v[8:9]
	v_pk_mul_f32 v[10:11], v[10:11], v[18:19]
	v_mul_f32_e32 v12, 0xbfb8aa3b, v0
	v_pk_mul_f32 v[10:11], v[14:15], v[10:11]
	v_mul_f32_e32 v13, 0xbfb8aa3b, v1
	v_mul_f32_e32 v14, 0xbfb8aa3b, v2
	v_mul_f32_e32 v15, 0xbfb8aa3b, v3
	v_exp_f32_e32 v12, v12
	v_exp_f32_e32 v13, v13
	v_exp_f32_e32 v14, v14
	v_exp_f32_e32 v15, v15
	v_add_f32_e32 v12, 1.0, v12
	v_add_f32_e32 v13, 1.0, v13
	v_add_f32_e32 v14, 1.0, v14
	v_add_f32_e32 v15, 1.0, v15
	v_rcp_f32_e32 v12, v12
	v_rcp_f32_e32 v13, v13
	v_rcp_f32_e32 v14, v14
	v_rcp_f32_e32 v15, v15
	v_pk_mul_f32 v[0:1], v[0:1], v[12:13]
	s_nop 0
	v_pk_mul_f32 v[0:1], v[4:5], v[0:1]
	v_pk_mul_f32 v[2:3], v[2:3], v[14:15]
	v_pk_mul_f32 v[4:5], v[106:107], v[114:115]
	v_pk_mul_f32 v[2:3], v[6:7], v[2:3]
	v_pk_mul_f32 v[6:7], v[104:105], v[112:113]
	v_pk_fma_f32 v[4:5], v[26:27], v[110:111], v[4:5]
	v_pk_fma_f32 v[6:7], v[24:25], v[108:109], v[6:7]
	v_pk_fma_f32 v[4:5], v[42:43], v[102:103], v[4:5]
	v_pk_fma_f32 v[6:7], v[40:41], v[100:101], v[6:7]
	v_pk_mul_f32 v[2:3], v[2:3], v[4:5]
	v_pk_mul_f32 v[0:1], v[0:1], v[6:7]
	v_cvt_pk_f16_f32 v3, v2, v3
	v_cvt_pk_f16_f32 v2, v0, v1
	v_add_u32_e32 v0, 0x41000, v56
	global_store_dwordx2 v0, v[2:3], s[84:85] sc1
	v_pk_mul_f32 v[0:1], v[98:99], v[114:115]
	v_pk_mul_f32 v[2:3], v[96:97], v[112:113]
	v_pk_fma_f32 v[0:1], v[106:107], v[110:111], v[0:1]
	v_pk_fma_f32 v[2:3], v[104:105], v[108:109], v[2:3]
	v_pk_fma_f32 v[0:1], v[26:27], v[102:103], v[0:1]
	v_pk_fma_f32 v[2:3], v[24:25], v[100:101], v[2:3]
	v_pk_mul_f32 v[0:1], v[10:11], v[0:1]
	v_pk_mul_f32 v[2:3], v[8:9], v[2:3]
	v_cvt_pk_f16_f32 v1, v0, v1
	v_cvt_pk_f16_f32 v0, v2, v3
	v_add_u32_e32 v2, 0x41800, v56
	global_store_dwordx2 v2, v[0:1], s[84:85] sc1
	s_andn2_b64 vcc, exec, s[8:9]
	s_mov_b64 s[0:1], -1
	s_cbranch_vccnz .LBB0_180
	s_branch .LBB0_303

.LBB0_237:
	v_lshlrev_b32_e32 v128, 10, v180
	s_and_b64 s[4:5], s[12:13], exec
	v_or3_b32 v128, v128, s53, v142
	s_cselect_b32 s4, 0x17e00000, s54
	v_lshl_or_b32 v129, v180, 8, v160
	v_lshlrev_b32_e32 v128, 1, v128
	s_cselect_b32 s5, 0, 0
	s_add_u32 s4, s76, s4
	v_cvt_pk_f16_f32 v155, v126, v127
	v_cvt_pk_f16_f32 v154, v124, v125
	v_cvt_pk_f16_f32 v153, v54, v55
	v_cvt_pk_f16_f32 v152, v52, v53
	v_cndmask_b32_e64 v129, v128, v129, s[12:13]
	s_addc_u32 s5, s77, s5
	s_and_b64 vcc, exec, s[10:11]
	global_store_dwordx4 v129, v[152:155], s[4:5] sc1
	s_cbranch_vccnz .LBB0_239
	s_nop 0
	v_cvt_pk_f16_f32 v155, v50, v51
	v_cvt_pk_f16_f32 v154, v48, v49
	v_cvt_pk_f16_f32 v153, v122, v123
	v_cvt_pk_f16_f32 v152, v120, v121
	global_store_dwordx4 v128, v[152:155], s[34:35] offset:256 sc1

.LBB0_244:
	s_or_b64 exec, exec, s[4:5]
	s_lshl_b32 s4, s16, 10
	s_cmp_lg_u32 s16, 3
	s_cselect_b32 s16, s4, 0xc80
	s_and_b64 vcc, exec, s[14:15]
	s_mov_b64 s[4:5], -1
	s_cbranch_vccnz .LBB0_248
	v_mul_f32_e32 v128, 0xbfb8aa3b, v56
	v_mul_f32_e32 v129, 0xbfb8aa3b, v57
	v_mul_f32_e32 v130, 0xbfb8aa3b, v58
	v_mul_f32_e32 v131, 0xbfb8aa3b, v59
	v_exp_f32_e32 v128, v128
	v_exp_f32_e32 v129, v129
	v_exp_f32_e32 v130, v130
	v_exp_f32_e32 v131, v131
	v_add_f32_e32 v128, 1.0, v128
	v_add_f32_e32 v129, 1.0, v129
	v_add_f32_e32 v130, 1.0, v130
	v_add_f32_e32 v131, 1.0, v131
	v_rcp_f32_e32 v128, v128
	v_rcp_f32_e32 v130, v130
	v_rcp_f32_e32 v131, v131
	v_rcp_f32_e32 v129, v129
	v_lshl_add_u32 v153, v180, 11, v179
	v_cmp_lt_i32_e32 vcc, -1, v154
	v_pk_mul_f32 v[130:131], v[58:59], v[130:131]
	v_pk_mul_f32 v[128:129], v[56:57], v[128:129]
	v_pk_mul_f32 v[182:183], v[62:63], v[130:131]
	v_pk_mul_f32 v[156:157], v[60:61], v[128:129]
	v_pk_mul_f32 v[130:131], v[118:119], v[114:115]
	v_pk_mul_f32 v[128:129], v[116:117], v[112:113]
	v_cvt_pk_f16_f32 v185, v130, v131
	v_cvt_pk_f16_f32 v184, v128, v129
	v_cvt_pk_f16_f32 v183, v182, v183
	v_cvt_pk_f16_f32 v182, v156, v157
	global_store_dwordx2 v153, v[184:185], s[0:1] sc1
	global_store_dwordx2 v153, v[182:183], s[38:39] sc1
	s_and_saveexec_b64 s[4:5], vcc
	s_cbranch_execz .LBB0_247
	v_readlane_b32 s56, v255, 0
	v_cndmask_b32_e64 v156, v175, v176, s[86:87]
	v_mov_b32_e32 v157, v141
	v_readlane_b32 s62, v255, 6
	v_readlane_b32 s63, v255, 7
	v_ashrrev_i32_e32 v153, 31, v152
	v_mov_b32_e32 v155, v141
	v_lshl_add_u64 v[156:157], s[62:63], 0, v[156:157]
	v_lshlrev_b64 v[182:183], 13, v[152:153]
	v_lshl_add_u64 v[156:157], v[156:157], 0, v[182:183]
	v_lshlrev_b64 v[182:183], 12, v[154:155]
	v_lshl_add_u64 v[156:157], v[156:157], 0, v[182:183]
	v_lshl_add_u64 v[156:157], v[140:141], 2, v[156:157]
	v_readlane_b32 s57, v255, 1
	v_readlane_b32 s58, v255, 2
	v_readlane_b32 s59, v255, 3
	v_readlane_b32 s60, v255, 4
	v_readlane_b32 s61, v255, 5
	global_store_dwordx4 v[156:157], v[128:131], off sc1

.LBB0_248:
	s_andn2_b64 vcc, exec, s[4:5]
	s_or_b32 s4, s16, s53
	s_cbranch_vccnz .LBB0_259
	v_lshl_or_b32 v153, v180, 10, s53
	v_cvt_pk_f16_f32 v131, v118, v119
	v_cvt_pk_f16_f32 v130, v116, v117
	v_cvt_pk_f16_f32 v129, v62, v63
	v_cvt_pk_f16_f32 v128, v60, v61
	s_and_b64 vcc, exec, s[10:11]
	s_mov_b64 s[16:17], -1
	s_cbranch_vccnz .LBB0_251
	v_or_b32_e32 v155, v153, v142
	v_lshlrev_b32_e32 v155, 1, v155
	v_or_b32_e32 v156, s4, v142
	s_mov_b64 s[16:17], 0
	global_store_dwordx4 v155, v[128:131], s[34:35] sc1
.LBB0_251:
	s_andn2_b64 vcc, exec, s[16:17]
	s_cbranch_vccnz .LBB0_253
	v_readlane_b32 s16, v255, 42
	v_lshl_or_b32 v155, v180, 8, v160
	v_readlane_b32 s17, v255, 43
	v_mov_b32_e32 v156, v161
	s_nop 3
	global_store_dwordx4 v155, v[128:131], s[16:17] sc1
.LBB0_253:
	s_movk_i32 s5, 0x4200
	v_cmp_eq_u32_e64 s[16:17], 1, v154
	v_cndmask_b32_e64 v130, v177, v178, s[86:87]
	v_mad_i64_i32 v[128:129], s[56:57], v152, s5, 0
	s_and_saveexec_b64 s[86:87], s[16:17]
	s_cbranch_execz .LBB0_255
	v_readlane_b32 s56, v255, 0
	v_lshlrev_b32_e32 v154, 2, v130
	v_mov_b32_e32 v155, v141
	v_readlane_b32 s62, v255, 6
	v_readlane_b32 s63, v255, 7
	v_ashrrev_i32_e32 v157, 31, v156
	v_readlane_b32 s57, v255, 1
	v_lshl_add_u64 v[154:155], s[62:63], 0, v[154:155]
	v_lshl_add_u64 v[154:155], v[154:155], 0, v[128:129]
	v_lshl_add_u64 v[154:155], v[156:157], 2, v[154:155]
	v_readlane_b32 s58, v255, 2
	v_readlane_b32 s59, v255, 3
	v_readlane_b32 s60, v255, 4
	v_readlane_b32 s61, v255, 5
	global_store_dwordx4 v[154:155], v[60:63], off sc1
	global_store_dwordx4 v[154:155], v[116:119], off offset:16 sc1
.LBB0_255:
	s_or_b64 exec, exec, s[86:87]
	s_and_b64 vcc, exec, s[10:11]
	s_cbranch_vccnz .LBB0_259
	v_or_b32_e32 v131, v153, v162
	v_cvt_pk_f16_f32 v157, v58, v59
	v_cvt_pk_f16_f32 v156, v56, v57
	v_cvt_pk_f16_f32 v155, v114, v115
	v_cvt_pk_f16_f32 v154, v112, v113
	v_lshlrev_b32_e32 v131, 1, v131
	global_store_dwordx4 v131, v[154:157], s[34:35] sc1
	s_and_saveexec_b64 s[86:87], s[16:17]
	s_cbranch_execz .LBB0_258
	v_readlane_b32 s56, v255, 0
	v_lshlrev_b32_e32 v130, 2, v130
	v_mov_b32_e32 v131, v141
	v_readlane_b32 s62, v255, 6
	v_readlane_b32 s63, v255, 7
	s_ashr_i32 s5, s4, 31
	v_readlane_b32 s57, v255, 1
	v_lshl_add_u64 v[130:131], s[62:63], 0, v[130:131]
	v_lshl_add_u64 v[128:129], v[130:131], 0, v[128:129]
	v_lshl_add_u64 v[130:131], s[4:5], 0, v[142:143]
	v_lshl_add_u64 v[128:129], v[130:131], 2, v[128:129]
	v_readlane_b32 s58, v255, 2
	v_readlane_b32 s59, v255, 3
	v_readlane_b32 s60, v255, 4
	v_readlane_b32 s61, v255, 5
	global_store_dwordx4 v[128:129], v[112:115], off offset:512 sc1
	global_store_dwordx4 v[128:129], v[56:59], off offset:528 sc1

.LBB0_259:
	s_addk_i32 s55, 0x80
	v_or_b32_e32 v156, s55, v158
	s_and_b64 vcc, exec, s[14:15]
	s_mov_b64 s[16:17], -1
	s_cbranch_vccnz .LBB0_261
	v_mul_f32_e32 v128, 0xbfb8aa3b, v28
	v_mul_f32_e32 v129, 0xbfb8aa3b, v29
	v_mul_f32_e32 v130, 0xbfb8aa3b, v30
	v_mul_f32_e32 v131, 0xbfb8aa3b, v31
	v_exp_f32_e32 v128, v128
	v_exp_f32_e32 v129, v129
	v_exp_f32_e32 v130, v130
	v_exp_f32_e32 v131, v131
	v_add_f32_e32 v128, 1.0, v128
	v_add_f32_e32 v129, 1.0, v129
	v_add_f32_e32 v130, 1.0, v130
	v_add_f32_e32 v131, 1.0, v131
	v_rcp_f32_e32 v128, v128
	v_rcp_f32_e32 v130, v130
	v_rcp_f32_e32 v131, v131
	v_rcp_f32_e32 v129, v129
	v_pk_mul_f32 v[152:153], v[46:47], v[42:43]
	v_pk_mul_f32 v[154:155], v[44:45], v[40:41]
	v_pk_mul_f32 v[130:131], v[30:31], v[130:131]
	v_pk_mul_f32 v[128:129], v[28:29], v[128:129]
	v_pk_mul_f32 v[130:131], v[38:39], v[130:131]
	v_pk_mul_f32 v[128:129], v[36:37], v[128:129]
	v_lshl_add_u32 v157, v156, 11, v179
	v_cvt_pk_f16_f32 v153, v152, v153
	v_cvt_pk_f16_f32 v152, v154, v155
	v_cvt_pk_f16_f32 v131, v130, v131
	v_cvt_pk_f16_f32 v130, v128, v129
	s_mov_b64 s[16:17], 0
	global_store_dwordx2 v157, v[152:153], s[0:1] sc1
	global_store_dwordx2 v157, v[130:131], s[38:39] sc1
.LBB0_261:
	s_andn2_b64 vcc, exec, s[16:17]
	s_movk_i32 s86, 0x7fff
	s_cbranch_vccnz .LBB0_264
	v_lshlrev_b32_e32 v128, 10, v156
	s_and_b64 s[16:17], s[12:13], exec
	v_or3_b32 v128, v128, s53, v142
	s_cselect_b32 s16, 0x17e00000, s54
	v_lshl_or_b32 v129, v156, 8, v160
	v_lshlrev_b32_e32 v128, 1, v128
	s_cselect_b32 s5, 0, 0
	s_add_u32 s16, s76, s16
	v_cvt_pk_f16_f32 v155, v46, v47
	v_cvt_pk_f16_f32 v154, v44, v45
	v_cvt_pk_f16_f32 v153, v38, v39
	v_cvt_pk_f16_f32 v152, v36, v37
	v_cndmask_b32_e64 v129, v128, v129, s[12:13]
	s_addc_u32 s17, s77, s5
	s_and_b64 vcc, exec, s[10:11]
	global_store_dwordx4 v129, v[152:155], s[16:17] sc1
	s_cbranch_vccnz .LBB0_264
	s_nop 0
	v_cvt_pk_f16_f32 v155, v30, v31
	v_cvt_pk_f16_f32 v154, v28, v29
	v_cvt_pk_f16_f32 v153, v42, v43
	v_cvt_pk_f16_f32 v152, v40, v41
	global_store_dwordx4 v128, v[152:155], s[34:35] offset:256 sc1
.LBB0_264:
	v_or_b32_e32 v128, 1, v156
	s_and_b64 vcc, exec, s[14:15]
	s_mov_b64 s[16:17], -1
	s_cbranch_vccnz .LBB0_266
	v_mul_f32_e32 v129, 0xbfb8aa3b, v16
	v_exp_f32_e32 v129, v129
	v_mul_f32_e32 v130, 0xbfb8aa3b, v17
	v_mul_f32_e32 v131, 0xbfb8aa3b, v18
	v_exp_f32_e32 v152, v130
	v_add_f32_e32 v129, 1.0, v129
	v_rcp_f32_e32 v130, v129
	v_exp_f32_e32 v129, v131
	v_mul_f32_e32 v131, 0xbfb8aa3b, v19
	v_exp_f32_e32 v131, v131
	v_add_f32_e32 v154, 1.0, v152
	v_add_f32_e32 v129, 1.0, v129
	v_rcp_f32_e32 v152, v129
	v_add_f32_e32 v129, 1.0, v131
	v_rcp_f32_e32 v153, v129
	v_rcp_f32_e32 v131, v154
	v_pk_mul_f32 v[154:155], v[34:35], v[26:27]
	v_pk_mul_f32 v[180:181], v[32:33], v[24:25]
	v_pk_mul_f32 v[152:153], v[18:19], v[152:153]
	v_pk_mul_f32 v[130:131], v[16:17], v[130:131]
	v_pk_mul_f32 v[152:153], v[22:23], v[152:153]
	v_pk_mul_f32 v[130:131], v[20:21], v[130:131]
	v_lshl_add_u32 v129, v128, 11, v179
	v_cvt_pk_f16_f32 v155, v154, v155
	v_cvt_pk_f16_f32 v154, v180, v181
	v_cvt_pk_f16_f32 v153, v152, v153
	v_cvt_pk_f16_f32 v152, v130, v131
	s_mov_b64 s[16:17], 0
	global_store_dwordx2 v129, v[154:155], s[0:1] sc1
	global_store_dwordx2 v129, v[152:153], s[38:39] sc1
.LBB0_266:
	s_andn2_b64 vcc, exec, s[16:17]
	s_cbranch_vccnz .LBB0_269
	v_lshlrev_b32_e32 v129, 10, v128
	s_and_b64 s[16:17], s[12:13], exec
	v_lshl_or_b32 v130, v128, 8, v160
	v_or3_b32 v128, v129, s53, v142
	s_cselect_b32 s16, 0x17e00000, s54
	v_lshlrev_b32_e32 v128, 1, v128
	s_cselect_b32 s5, 0, 0
	s_add_u32 s16, s76, s16
	v_cvt_pk_f16_f32 v155, v34, v35
	v_cvt_pk_f16_f32 v154, v32, v33
	v_cvt_pk_f16_f32 v153, v22, v23
	v_cvt_pk_f16_f32 v152, v20, v21
	v_cndmask_b32_e64 v129, v128, v130, s[12:13]
	s_addc_u32 s17, s77, s5
	s_and_b64 vcc, exec, s[10:11]
	global_store_dwordx4 v129, v[152:155], s[16:17] sc1
	s_cbranch_vccnz .LBB0_269
	s_nop 0
	v_cvt_pk_f16_f32 v155, v18, v19
	v_cvt_pk_f16_f32 v154, v16, v17
	v_cvt_pk_f16_f32 v153, v26, v27
	v_cvt_pk_f16_f32 v152, v24, v25
	global_store_dwordx4 v128, v[152:155], s[34:35] offset:256 sc1

.LBB0_273:
	v_mul_f32_e32 v128, 0xbfb8aa3b, v0
	v_mul_f32_e32 v129, 0xbfb8aa3b, v1
	v_mul_f32_e32 v130, 0xbfb8aa3b, v2
	v_mul_f32_e32 v131, 0xbfb8aa3b, v3
	v_exp_f32_e32 v128, v128
	v_exp_f32_e32 v129, v129
	v_exp_f32_e32 v130, v130
	v_exp_f32_e32 v131, v131
	v_add_f32_e32 v128, 1.0, v128
	v_add_f32_e32 v129, 1.0, v129
	v_add_f32_e32 v130, 1.0, v130
	v_add_f32_e32 v131, 1.0, v131
	v_rcp_f32_e32 v128, v128
	v_rcp_f32_e32 v130, v130
	v_rcp_f32_e32 v131, v131
	v_rcp_f32_e32 v129, v129
	v_lshl_add_u32 v181, v180, 11, v179
	v_cmp_lt_i32_e32 vcc, -1, v153
	v_pk_mul_f32 v[130:131], v[2:3], v[130:131]
	v_pk_mul_f32 v[128:129], v[0:1], v[128:129]
	v_pk_mul_f32 v[184:185], v[6:7], v[130:131]
	v_pk_mul_f32 v[182:183], v[4:5], v[128:129]
	v_pk_mul_f32 v[130:131], v[110:111], v[106:107]
	v_pk_mul_f32 v[128:129], v[108:109], v[104:105]
	v_cvt_pk_f16_f32 v187, v130, v131
	v_cvt_pk_f16_f32 v186, v128, v129
	v_cvt_pk_f16_f32 v185, v184, v185
	v_cvt_pk_f16_f32 v184, v182, v183
	global_store_dwordx2 v181, v[186:187], s[0:1] sc1
	global_store_dwordx2 v181, v[184:185], s[38:39] sc1
	s_and_saveexec_b64 s[16:17], vcc
	s_cbranch_execz .LBB0_275
	v_readlane_b32 s56, v255, 0
	v_readlane_b32 s62, v255, 6
	v_readlane_b32 s63, v255, 7
	v_ashrrev_i32_e32 v153, 31, v152
	v_lshlrev_b64 v[152:153], 13, v[152:153]
	v_lshl_add_u64 v[154:155], v[154:155], 2, s[62:63]
	v_lshl_add_u64 v[152:153], v[154:155], 0, v[152:153]
	v_lshl_add_u64 v[152:153], v[140:141], 2, v[152:153]
	v_readlane_b32 s57, v255, 1
	v_readlane_b32 s58, v255, 2
	v_readlane_b32 s59, v255, 3
	v_readlane_b32 s60, v255, 4
	v_readlane_b32 s61, v255, 5
	global_store_dwordx4 v[152:153], v[128:131], off sc1

.LBB0_279:
	v_lshlrev_b32_e32 v128, 10, v180
	v_or3_b32 v128, v128, s53, v142
	v_lshl_or_b32 v129, v180, 8, v160
	v_lshlrev_b32_e32 v128, 1, v128
	v_cndmask_b32_e64 v129, v128, v129, s[12:13]
	s_and_b64 s[12:13], s[12:13], exec
	s_cselect_b32 s12, 0x17e00000, s54
	s_cselect_b32 s13, 0, 0
	s_add_u32 s12, s76, s12
	v_cvt_pk_f16_f32 v155, v110, v111
	v_cvt_pk_f16_f32 v154, v108, v109
	v_cvt_pk_f16_f32 v153, v6, v7
	v_cvt_pk_f16_f32 v152, v4, v5
	s_addc_u32 s13, s77, s13
	s_and_b64 vcc, exec, s[10:11]
	global_store_dwordx4 v129, v[152:155], s[12:13] sc1
	s_cbranch_vccnz .LBB0_281
	s_nop 0
	v_cvt_pk_f16_f32 v155, v2, v3
	v_cvt_pk_f16_f32 v154, v0, v1
	v_cvt_pk_f16_f32 v153, v106, v107
	v_cvt_pk_f16_f32 v152, v104, v105
	global_store_dwordx4 v128, v[152:155], s[34:35] offset:256 sc1

.LBB0_285:
	v_mul_f32_e32 v128, 0xbfb8aa3b, v8
	v_mul_f32_e32 v129, 0xbfb8aa3b, v9
	v_mul_f32_e32 v130, 0xbfb8aa3b, v10
	v_mul_f32_e32 v131, 0xbfb8aa3b, v11
	v_exp_f32_e32 v128, v128
	v_exp_f32_e32 v129, v129
	v_exp_f32_e32 v130, v130
	v_exp_f32_e32 v131, v131
	v_add_f32_e32 v128, 1.0, v128
	v_add_f32_e32 v129, 1.0, v129
	v_add_f32_e32 v130, 1.0, v130
	v_add_f32_e32 v131, 1.0, v131
	v_rcp_f32_e32 v128, v128
	v_rcp_f32_e32 v130, v130
	v_rcp_f32_e32 v131, v131
	v_rcp_f32_e32 v129, v129
	v_lshl_add_u32 v153, v180, 11, v179
	v_cmp_lt_i32_e32 vcc, -1, v154
	v_pk_mul_f32 v[130:131], v[10:11], v[130:131]
	v_pk_mul_f32 v[128:129], v[8:9], v[128:129]
	v_pk_mul_f32 v[182:183], v[14:15], v[130:131]
	v_pk_mul_f32 v[156:157], v[12:13], v[128:129]
	v_pk_mul_f32 v[130:131], v[102:103], v[98:99]
	v_pk_mul_f32 v[128:129], v[100:101], v[96:97]
	v_cvt_pk_f16_f32 v185, v130, v131
	v_cvt_pk_f16_f32 v184, v128, v129
	v_cvt_pk_f16_f32 v183, v182, v183
	v_cvt_pk_f16_f32 v182, v156, v157
	global_store_dwordx2 v153, v[184:185], s[0:1] sc1
	global_store_dwordx2 v153, v[182:183], s[38:39] sc1
	s_and_saveexec_b64 s[0:1], vcc
	s_cbranch_execz .LBB0_287
	v_readlane_b32 s56, v255, 0
	v_cndmask_b32_e64 v156, v175, v176, s[16:17]
	v_mov_b32_e32 v157, v141
	v_readlane_b32 s62, v255, 6
	v_readlane_b32 s63, v255, 7
	v_ashrrev_i32_e32 v153, 31, v152
	v_mov_b32_e32 v155, v141
	v_lshl_add_u64 v[156:157], s[62:63], 0, v[156:157]
	v_lshlrev_b64 v[182:183], 13, v[152:153]
	v_lshl_add_u64 v[156:157], v[156:157], 0, v[182:183]
	v_lshlrev_b64 v[182:183], 12, v[154:155]
	v_lshl_add_u64 v[156:157], v[156:157], 0, v[182:183]
	v_lshl_add_u64 v[156:157], v[140:141], 2, v[156:157]
	v_readlane_b32 s57, v255, 1
	v_readlane_b32 s58, v255, 2
	v_readlane_b32 s59, v255, 3
	v_readlane_b32 s60, v255, 4
	v_readlane_b32 s61, v255, 5
	global_store_dwordx4 v[156:157], v[128:131], off sc1

.LBB0_291:
	v_lshl_or_b32 v153, v180, 10, s53
	v_cvt_pk_f16_f32 v131, v102, v103
	v_cvt_pk_f16_f32 v130, v100, v101
	v_cvt_pk_f16_f32 v129, v14, v15
	v_cvt_pk_f16_f32 v128, v12, v13
	s_and_b64 vcc, exec, s[10:11]
	s_mov_b64 s[0:1], -1
	s_cbranch_vccnz .LBB0_293
	v_or_b32_e32 v140, v153, v142
	v_lshlrev_b32_e32 v140, 1, v140
	v_or_b32_e32 v156, s4, v142
	s_mov_b64 s[0:1], 0
	global_store_dwordx4 v140, v[128:131], s[34:35] sc1
.LBB0_293:
	s_andn2_b64 vcc, exec, s[0:1]
	s_cbranch_vccnz .LBB0_295
	v_readlane_b32 s0, v255, 42
	v_lshl_or_b32 v140, v180, 8, v160
	v_readlane_b32 s1, v255, 43
	v_mov_b32_e32 v156, v161
	s_nop 3
	global_store_dwordx4 v140, v[128:131], s[0:1] sc1
.LBB0_295:
	s_movk_i32 s0, 0x4200
	v_cmp_eq_u32_e64 s[12:13], 1, v154
	v_cndmask_b32_e64 v130, v177, v178, s[16:17]
	v_mad_i64_i32 v[128:129], s[0:1], v152, s0, 0
	s_and_saveexec_b64 s[0:1], s[12:13]
	s_cbranch_execz .LBB0_297
	v_readlane_b32 s56, v255, 0
	v_lshlrev_b32_e32 v140, 2, v130
	v_readlane_b32 s62, v255, 6
	v_readlane_b32 s63, v255, 7
	v_ashrrev_i32_e32 v157, 31, v156
	v_readlane_b32 s57, v255, 1
	v_lshl_add_u64 v[154:155], s[62:63], 0, v[140:141]
	v_lshl_add_u64 v[154:155], v[154:155], 0, v[128:129]
	v_lshl_add_u64 v[154:155], v[156:157], 2, v[154:155]
	v_readlane_b32 s58, v255, 2
	v_readlane_b32 s59, v255, 3
	v_readlane_b32 s60, v255, 4
	v_readlane_b32 s61, v255, 5
	global_store_dwordx4 v[154:155], v[12:15], off sc1
	global_store_dwordx4 v[154:155], v[100:103], off offset:16 sc1
.LBB0_297:
	s_or_b64 exec, exec, s[0:1]
	s_and_b64 vcc, exec, s[10:11]
	s_cbranch_vccnz .LBB0_301
	v_or_b32_e32 v131, v153, v162
	v_cvt_pk_f16_f32 v157, v10, v11
	v_cvt_pk_f16_f32 v156, v8, v9
	v_cvt_pk_f16_f32 v155, v98, v99
	v_cvt_pk_f16_f32 v154, v96, v97
	v_lshlrev_b32_e32 v131, 1, v131
	global_store_dwordx4 v131, v[154:157], s[34:35] sc1
	s_and_saveexec_b64 s[0:1], s[12:13]
	s_cbranch_execz .LBB0_300
	v_readlane_b32 s56, v255, 0
	v_lshlrev_b32_e32 v140, 2, v130
	v_readlane_b32 s62, v255, 6
	v_readlane_b32 s63, v255, 7
	s_ashr_i32 s5, s4, 31
	v_readlane_b32 s57, v255, 1
	v_lshl_add_u64 v[130:131], s[62:63], 0, v[140:141]
	v_lshl_add_u64 v[128:129], v[130:131], 0, v[128:129]
	v_lshl_add_u64 v[130:131], s[4:5], 0, v[142:143]
	v_lshl_add_u64 v[128:129], v[130:131], 2, v[128:129]
	v_readlane_b32 s58, v255, 2
	v_readlane_b32 s59, v255, 3
	v_readlane_b32 s60, v255, 4
	v_readlane_b32 s61, v255, 5
	global_store_dwordx4 v[128:129], v[96:99], off offset:512 sc1
	global_store_dwordx4 v[128:129], v[8:11], off offset:528 sc1
